# FFN1-in / FFN2-in epilogues: write-through stores only for the workgroup's last tile of the phase, plain stores for earlier tiles (exec-masked store pairs)
# baseline (speedup 1.0000x reference)
.LBB0_400:
	s_add_i32 s36, s36, 1
	s_mul_i32 s0, s36, s85
	s_mul_hi_u32 s1, s36, s84
	s_add_i32 s1, s1, s0
	s_mul_i32 s0, s36, s84
	s_add_u32 s10, s0, s13
	s_addc_u32 s11, s1, s27
	v_cmp_gt_i64_e32 vcc, s[10:11], v[238:239]
	v_mov_b64_e32 v[230:231], 0xff
	v_cmp_lt_i64_e64 s[0:1], s[10:11], v[234:235]
	s_mov_b64 s[100:101], s[0:1]
	s_not_b64 s[98:99], s[0:1]
	s_cbranch_vccnz .LBB0_402
	s_ashr_i32 s6, s10, 31
	s_lshr_b32 s6, s6, 29
	s_add_i32 s6, s10, s6
	s_ashr_i32 s7, s6, 3
	s_and_b32 s6, s6, -8
	s_sub_i32 s6, s10, s6
	s_cmp_lt_i32 s6, 0
	s_cselect_b32 s8, s57, 0xb0
	s_mul_i32 s6, s6, s8
	s_add_i32 s6, s6, s7
	s_mul_hi_i32 s7, s6, 0x2e8ba2e9
	s_lshr_b32 s8, s7, 31
	s_ashr_i32 s7, s7, 5
	s_add_i32 s7, s7, s8
	s_lshl_b32 s8, s7, 3
	s_sub_i32 s9, 64, s8
	s_min_i32 s9, s9, 8
	s_abs_i32 s10, s9
	v_cvt_f32_u32_e32 v2, s10
	s_sub_i32 s14, 0, s10
	s_mulk_i32 s7, 0xb0
	s_sub_i32 s7, s6, s7
	v_rcp_iflag_f32_e32 v2, v2
	s_abs_i32 s6, s7
	s_xor_b32 s11, s7, s9
	s_ashr_i32 s11, s11, 31
	v_mul_f32_e32 v2, 0x4f7ffffe, v2
	v_cvt_u32_f32_e32 v2, v2
	s_nop 0
	v_readfirstlane_b32 s15, v2
	s_mul_i32 s14, s14, s15
	s_mul_hi_u32 s14, s15, s14
	s_add_i32 s15, s15, s14
	s_mul_hi_u32 s14, s6, s15
	s_mul_i32 s15, s14, s10
	s_sub_i32 s6, s6, s15
	s_add_i32 s22, s14, 1
	s_sub_i32 s15, s6, s10
	s_cmp_ge_u32 s6, s10
	s_cselect_b32 s14, s22, s14
	s_cselect_b32 s6, s15, s6
	s_add_i32 s15, s14, 1
	s_cmp_ge_u32 s6, s10
	s_cselect_b32 s6, s15, s14
	s_xor_b32 s6, s6, s11
	s_sub_i32 s6, s6, s11
	s_mul_i32 s9, s6, s9
	s_sub_i32 s7, s7, s9
	s_add_i32 s8, s8, s7

.LBB0_406:
	s_mov_b32 s7, s33
	v_lshl_or_b32 v190, s17, 7, v175
	v_mov_b32_e32 v130, s7
	ds_read2_b32 v[130:131], v130 offset1:1
	s_ashr_i32 s17, s16, 31
	s_lshl_b64 s[16:17], s[16:17], 8
	v_lshl_add_u64 v[170:171], s[16:17], 0, v[158:159]
	v_lshlrev_b64 v[132:133], 6, v[170:171]
	s_waitcnt lgkmcnt(0)
	v_readfirstlane_b32 s7, v130
	v_readfirstlane_b32 s9, v131
	v_mov_b32_e32 v186, s7
	s_mov_b32 s7, s33
	v_mov_b32_e32 v187, s9
	v_mov_b32_e32 v130, s7
	ds_read2_b32 v[130:131], v130 offset1:1
	v_ashrrev_i32_e32 v191, 31, v190
	v_mov_b64_e32 v[218:219], v[230:231]
	s_waitcnt lgkmcnt(0)
	v_readfirstlane_b32 s18, v130
	v_readfirstlane_b32 s19, v131
	s_nop 1
	v_lshl_add_u64 v[130:131], s[18:19], 0, v[0:1]
	v_lshl_add_u64 v[130:131], v[130:131], 0, v[132:133]
	v_add_co_u32_e32 v134, vcc, s58, v130
	s_mov_b64 s[18:19], 0x10380000
	s_nop 0
	v_addc_co_u32_e32 v135, vcc, 0, v131, vcc
	v_lshl_add_u64 v[132:133], v[130:131], 0, s[18:19]
	global_load_dwordx4 v[192:195], v[134:135], off
	global_load_dwordx4 v[196:199], v[132:133], off offset:1024
	global_load_dwordx4 v[200:203], v[132:133], off offset:2048
	global_load_dwordx4 v[146:149], v[132:133], off offset:3072
	v_add_co_u32_e32 v130, vcc, s59, v130
	s_mov_b64 s[18:19], 0xaa00000
	s_nop 0
	v_addc_co_u32_e32 v131, vcc, 0, v131, vcc
	global_load_dwordx4 v[142:145], v[130:131], off
	global_load_dwordx4 v[138:141], v[130:131], off offset:1024
	global_load_dwordx4 v[134:137], v[130:131], off offset:2048
	s_nop 0
	global_load_dwordx4 v[130:133], v[130:131], off offset:3072
	s_andn2_b64 vcc, exec, s[0:1]
	s_waitcnt vmcnt(0)
	v_mov_b32_e32 v176, v193
	v_mov_b32_e32 v177, v194
	v_mov_b32_e32 v193, v195
	v_pk_add_f32 v[176:177], v[176:177], v[192:193]
	s_nop 0
	v_add_f32_e32 v172, v176, v177
	v_mov_b32_e32 v174, v172
	s_nop 1
	v_permlane16_swap_b32_e32 v174, v172
	v_mov_b32_e32 v176, v197
	v_mov_b32_e32 v177, v198
	v_mov_b32_e32 v197, v199
	v_pk_add_f32 v[176:177], v[176:177], v[196:197]
	s_waitcnt lgkmcnt(0)
	v_add_f32_e32 v172, v172, v174
	s_nop 0
	v_mov_b32_e32 v174, v172
	s_nop 1
	v_permlane32_swap_b32_e32 v174, v172
	s_waitcnt lgkmcnt(0)
	v_add_f32_e32 v172, v172, v174
	v_fmamk_f32 v172, v172, 0x3a800000, v228
	v_rsq_f32_e32 v188, v172
	v_add_f32_e32 v172, v176, v177
	v_mov_b32_e32 v174, v172
	s_nop 1
	v_permlane16_swap_b32_e32 v174, v172
	v_mov_b32_e32 v176, v201
	v_mov_b32_e32 v177, v202
	v_mov_b32_e32 v201, v203
	v_pk_add_f32 v[176:177], v[176:177], v[200:201]
	s_waitcnt lgkmcnt(0)
	v_add_f32_e32 v172, v172, v174
	v_pk_mul_f32 v[126:127], v[126:127], v[188:189] op_sel_hi:[1,0]
	v_mov_b32_e32 v174, v172
	s_nop 1
	v_permlane32_swap_b32_e32 v174, v172
	v_pk_mul_f32 v[122:123], v[122:123], v[188:189] op_sel_hi:[1,0]
	v_pk_mul_f32 v[124:125], v[124:125], v[188:189] op_sel_hi:[1,0]
	v_pk_mul_f32 v[118:119], v[118:119], v[188:189] op_sel_hi:[1,0]
	v_pk_mul_f32 v[114:115], v[114:115], v[188:189] op_sel_hi:[1,0]
	s_waitcnt lgkmcnt(0)
	v_add_f32_e32 v172, v172, v174
	v_fmamk_f32 v172, v172, 0x3a800000, v228
	v_rsq_f32_e32 v174, v172
	v_add_f32_e32 v172, v176, v177
	v_mov_b32_e32 v177, v148
	v_mov_b32_e32 v176, v172
	s_nop 1
	v_permlane16_swap_b32_e32 v176, v172
	v_mov_b32_e32 v148, v143
	v_mov_b32_e32 v143, v145
	v_mov_b32_e32 v145, v140
	v_mov_b32_e32 v140, v135
	s_waitcnt lgkmcnt(0)
	v_add_f32_e32 v172, v172, v176
	v_mov_b32_e32 v135, v137
	v_mov_b32_e32 v176, v172
	s_nop 1
	v_permlane32_swap_b32_e32 v176, v172
	v_mov_b32_e32 v137, v132
	v_pk_mul_f32 v[116:117], v[116:117], v[188:189] op_sel_hi:[1,0]
	v_pk_mul_f32 v[110:111], v[110:111], v[174:175] op_sel_hi:[1,0]
	v_pk_mul_f32 v[106:107], v[106:107], v[174:175] op_sel_hi:[1,0]
	s_waitcnt lgkmcnt(0)
	v_add_f32_e32 v172, v172, v176
	v_mov_b32_e32 v176, v147
	v_mov_b32_e32 v147, v149
	v_pk_add_f32 v[146:147], v[176:177], v[146:147]
	v_mov_b32_e32 v149, v144
	v_add_f32_e32 v146, v146, v147
	v_pk_add_f32 v[142:143], v[148:149], v[142:143]
	v_mov_b32_e32 v147, v146
	s_nop 1
	v_permlane16_swap_b32_e32 v147, v146
	v_add_f32_e32 v142, v142, v143
	v_mov_b32_e32 v144, v139
	v_mov_b32_e32 v139, v141
	s_waitcnt lgkmcnt(0)
	v_add_f32_e32 v146, v146, v147
	v_mov_b32_e32 v147, v1
	v_mov_b32_e32 v141, v136
	v_mov_b32_e32 v143, v142
	s_nop 1
	v_permlane16_swap_b32_e32 v143, v142
	v_mov_b32_e32 v136, v131
	v_mov_b32_e32 v131, v133
	v_mul_f32_e32 v133, 0xbfb8aa3b, v126
	v_exp_f32_e32 v133, v133
	v_pk_add_f32 v[138:139], v[144:145], v[138:139]
	s_waitcnt lgkmcnt(0)
	v_add_f32_e32 v142, v142, v143
	v_mov_b32_e32 v143, v1
	v_add_f32_e32 v138, v138, v139
	v_add_f32_e32 v133, 1.0, v133
	v_pk_add_f32 v[130:131], v[136:137], v[130:131]
	v_rcp_f32_e32 v136, v133
	v_mul_f32_e32 v133, 0xbfb8aa3b, v127
	v_exp_f32_e32 v133, v133
	v_mov_b32_e32 v139, v138
	s_nop 1
	v_permlane16_swap_b32_e32 v139, v138
	v_add_f32_e32 v133, 1.0, v133
	v_rcp_f32_e32 v137, v133
	v_pk_add_f32 v[134:135], v[140:141], v[134:135]
	v_add_f32_e32 v130, v130, v131
	s_waitcnt lgkmcnt(0)
	v_add_f32_e32 v138, v138, v139
	v_mov_b32_e32 v139, v1
	v_add_f32_e32 v134, v134, v135
	v_pk_mul_f32 v[126:127], v[126:127], v[136:137]
	v_pk_mul_f32 v[122:123], v[122:123], v[126:127]
	v_pk_mul_f32 v[126:127], v[128:129], v[188:189] op_sel_hi:[1,0]
	v_mul_f32_e32 v128, 0xbfb8aa3b, v126
	v_mul_f32_e32 v129, 0xbfb8aa3b, v127
	v_exp_f32_e32 v128, v128
	v_exp_f32_e32 v129, v129
	v_mov_b32_e32 v135, v134
	s_nop 1
	v_permlane16_swap_b32_e32 v135, v134
	v_add_f32_e32 v128, 1.0, v128
	v_add_f32_e32 v129, 1.0, v129
	v_rcp_f32_e32 v128, v128
	v_rcp_f32_e32 v129, v129
	s_waitcnt lgkmcnt(0)
	v_add_f32_e32 v134, v134, v135
	v_mov_b32_e32 v135, v1
	v_pk_mul_f32 v[126:127], v[126:127], v[128:129]
	v_pk_mul_f32 v[124:125], v[124:125], v[126:127]
	v_mul_f32_e32 v126, 0xbfb8aa3b, v118
	v_mul_f32_e32 v127, 0xbfb8aa3b, v119
	v_exp_f32_e32 v126, v126
	v_exp_f32_e32 v127, v127
	v_mov_b32_e32 v131, v130
	s_nop 1
	v_permlane16_swap_b32_e32 v131, v130
	v_add_f32_e32 v126, 1.0, v126
	v_add_f32_e32 v127, 1.0, v127
	v_rcp_f32_e32 v126, v126
	v_rcp_f32_e32 v127, v127
	s_waitcnt lgkmcnt(0)
	v_add_f32_e32 v130, v130, v131
	v_pk_mul_f32 v[118:119], v[118:119], v[126:127]
	v_pk_mul_f32 v[118:119], v[114:115], v[118:119]
	v_pk_mul_f32 v[114:115], v[120:121], v[188:189] op_sel_hi:[1,0]
	v_mul_f32_e32 v120, 0xbfb8aa3b, v114
	v_mul_f32_e32 v121, 0xbfb8aa3b, v115
	v_exp_f32_e32 v120, v120
	v_exp_f32_e32 v121, v121
	v_mov_b32_e32 v131, v130
	s_nop 1
	v_permlane32_swap_b32_e32 v131, v130
	v_pk_mul_f32 v[108:109], v[108:109], v[174:175] op_sel_hi:[1,0]
	v_add_f32_e32 v120, 1.0, v120
	v_add_f32_e32 v121, 1.0, v121
	v_rcp_f32_e32 v120, v120
	v_rcp_f32_e32 v121, v121
	s_waitcnt lgkmcnt(0)
	v_add_f32_e32 v130, v130, v131
	v_fmamk_f32 v130, v130, 0x3a800000, v228
	v_rsq_f32_e32 v132, v130
	v_lshl_add_u64 v[130:131], v[190:191], 1, v[186:187]
	v_lshl_add_u64 v[130:131], v[130:131], 0, s[18:19]
	v_pk_mul_f32 v[114:115], v[114:115], v[120:121]
	v_pk_mul_f32 v[102:103], v[102:103], v[174:175] op_sel_hi:[1,0]
	v_pk_mul_f32 v[120:121], v[116:117], v[114:115]
	v_cvt_pk_bf16_f32 v116, v118, v119
	v_mad_u64_u32 v[118:119], s[18:19], v170, s89, v[130:131]
	v_cvt_pk_bf16_f32 v117, v120, v121
	v_mov_b32_e32 v120, v119
	v_mad_u64_u32 v[120:121], s[18:19], v171, s89, v[120:121]
	v_cvt_pk_bf16_f32 v114, v122, v123
	v_cvt_pk_bf16_f32 v115, v124, v125
	v_mov_b32_e32 v119, v120
	s_mov_b64 exec, s[98:99]
	global_store_dwordx4 v[118:119], v[114:117], off sc1
	s_mov_b64 exec, s[100:101]
	global_store_dwordx4 v[118:119], v[114:117], off
	s_mov_b64 exec, -1
	v_pk_mul_f32 v[98:99], v[98:99], v[174:175] op_sel_hi:[1,0]
	v_fmamk_f32 v172, v172, 0x3a800000, v228
	v_mul_f32_e32 v114, 0xbfb8aa3b, v110
	v_mul_f32_e32 v115, 0xbfb8aa3b, v111
	v_exp_f32_e32 v114, v114
	v_exp_f32_e32 v115, v115
	v_rsq_f32_e32 v172, v172
	v_pk_mul_f32 v[100:101], v[100:101], v[174:175] op_sel_hi:[1,0]
	v_add_f32_e32 v114, 1.0, v114
	v_add_f32_e32 v115, 1.0, v115
	v_rcp_f32_e32 v114, v114
	v_rcp_f32_e32 v115, v115
	v_pk_mul_f32 v[94:95], v[94:95], v[172:173] op_sel_hi:[1,0]
	v_pk_mul_f32 v[90:91], v[90:91], v[172:173] op_sel_hi:[1,0]
	v_pk_mul_f32 v[92:93], v[92:93], v[172:173] op_sel_hi:[1,0]
	v_pk_mul_f32 v[110:111], v[110:111], v[114:115]
	v_pk_mul_f32 v[86:87], v[86:87], v[172:173] op_sel_hi:[1,0]
	v_pk_mul_f32 v[106:107], v[106:107], v[110:111]
	v_pk_mul_f32 v[110:111], v[112:113], v[174:175] op_sel_hi:[1,0]
	v_pk_mul_f32 v[82:83], v[82:83], v[172:173] op_sel_hi:[1,0]
	v_mul_f32_e32 v112, 0xbfb8aa3b, v110
	v_mul_f32_e32 v113, 0xbfb8aa3b, v111
	v_exp_f32_e32 v112, v112
	v_exp_f32_e32 v113, v113
	v_mbcnt_lo_u32_b32 v147, -1, v147
	v_mbcnt_hi_u32_b32 v147, -1, v147
	v_add_f32_e32 v112, 1.0, v112
	v_add_f32_e32 v113, 1.0, v113
	v_rcp_f32_e32 v112, v112
	v_rcp_f32_e32 v113, v113
	v_lshlrev_b32_e32 v147, 2, v147
	v_xor_b32_e32 v147, 0x80, v147
	ds_bpermute_b32 v147, v147, v146
	v_pk_mul_f32 v[110:111], v[110:111], v[112:113]
	v_pk_mul_f32 v[84:85], v[84:85], v[172:173] op_sel_hi:[1,0]
	v_pk_mul_f32 v[108:109], v[108:109], v[110:111]
	v_mul_f32_e32 v110, 0xbfb8aa3b, v102
	v_mul_f32_e32 v111, 0xbfb8aa3b, v103
	v_exp_f32_e32 v110, v110
	v_exp_f32_e32 v111, v111
	s_waitcnt lgkmcnt(0)
	v_add_f32_e32 v146, v146, v147
	v_fmamk_f32 v146, v146, 0x3a800000, v228
	v_add_f32_e32 v110, 1.0, v110
	v_add_f32_e32 v111, 1.0, v111
	v_rcp_f32_e32 v110, v110
	v_rcp_f32_e32 v111, v111
	v_rsq_f32_e32 v146, v146
	v_mbcnt_lo_u32_b32 v143, -1, v143
	v_mbcnt_hi_u32_b32 v143, -1, v143
	v_pk_mul_f32 v[102:103], v[102:103], v[110:111]
	v_lshl_add_u64 v[110:111], v[160:161], 0, s[16:17]
	v_pk_mul_f32 v[102:103], v[98:99], v[102:103]
	v_pk_mul_f32 v[98:99], v[104:105], v[174:175] op_sel_hi:[1,0]
	v_pk_mul_f32 v[78:79], v[78:79], v[146:147] op_sel_hi:[1,0]
	v_mul_f32_e32 v104, 0xbfb8aa3b, v98
	v_mul_f32_e32 v105, 0xbfb8aa3b, v99
	v_exp_f32_e32 v104, v104
	v_exp_f32_e32 v105, v105
	v_pk_mul_f32 v[74:75], v[74:75], v[146:147] op_sel_hi:[1,0]
	v_pk_mul_f32 v[76:77], v[76:77], v[146:147] op_sel_hi:[1,0]
	v_add_f32_e32 v104, 1.0, v104
	v_add_f32_e32 v105, 1.0, v105
	v_rcp_f32_e32 v104, v104
	v_rcp_f32_e32 v105, v105
	v_pk_mul_f32 v[70:71], v[70:71], v[146:147] op_sel_hi:[1,0]
	v_pk_mul_f32 v[66:67], v[66:67], v[146:147] op_sel_hi:[1,0]
	v_lshlrev_b32_e32 v143, 2, v143
	v_pk_mul_f32 v[98:99], v[98:99], v[104:105]
	v_xor_b32_e32 v143, 0x80, v143
	v_pk_mul_f32 v[104:105], v[100:101], v[98:99]
	v_cvt_pk_bf16_f32 v100, v102, v103
	v_mad_u64_u32 v[102:103], s[18:19], v110, s89, v[130:131]
	v_cvt_pk_bf16_f32 v101, v104, v105
	v_mov_b32_e32 v104, v103
	v_mad_u64_u32 v[104:105], s[18:19], v111, s89, v[104:105]
	v_cvt_pk_bf16_f32 v98, v106, v107
	v_cvt_pk_bf16_f32 v99, v108, v109
	v_mov_b32_e32 v103, v104
	s_mov_b64 exec, s[98:99]
	global_store_dwordx4 v[102:103], v[98:101], off sc1
	s_mov_b64 exec, s[100:101]
	global_store_dwordx4 v[102:103], v[98:101], off
	s_mov_b64 exec, -1
	ds_bpermute_b32 v143, v143, v142
	v_pk_mul_f32 v[68:69], v[68:69], v[146:147] op_sel_hi:[1,0]
	v_mul_f32_e32 v98, 0xbfb8aa3b, v94
	v_mul_f32_e32 v99, 0xbfb8aa3b, v95
	v_exp_f32_e32 v98, v98
	v_exp_f32_e32 v99, v99
	s_waitcnt lgkmcnt(0)
	v_add_f32_e32 v142, v142, v143
	v_fmamk_f32 v142, v142, 0x3a800000, v228
	v_add_f32_e32 v98, 1.0, v98
	v_add_f32_e32 v99, 1.0, v99
	v_rcp_f32_e32 v98, v98
	v_rcp_f32_e32 v99, v99
	v_rsq_f32_e32 v142, v142
	v_mbcnt_lo_u32_b32 v139, -1, v139
	v_mbcnt_hi_u32_b32 v139, -1, v139
	v_pk_mul_f32 v[94:95], v[94:95], v[98:99]
	v_pk_mul_f32 v[62:63], v[62:63], v[142:143] op_sel_hi:[1,0]
	v_pk_mul_f32 v[90:91], v[90:91], v[94:95]
	v_pk_mul_f32 v[94:95], v[96:97], v[172:173] op_sel_hi:[1,0]
	v_pk_mul_f32 v[58:59], v[58:59], v[142:143] op_sel_hi:[1,0]
	v_mul_f32_e32 v96, 0xbfb8aa3b, v94
	v_mul_f32_e32 v97, 0xbfb8aa3b, v95
	v_exp_f32_e32 v96, v96
	v_exp_f32_e32 v97, v97
	v_pk_mul_f32 v[60:61], v[60:61], v[142:143] op_sel_hi:[1,0]
	v_pk_mul_f32 v[54:55], v[54:55], v[142:143] op_sel_hi:[1,0]
	v_add_f32_e32 v96, 1.0, v96
	v_add_f32_e32 v97, 1.0, v97
	v_rcp_f32_e32 v96, v96
	v_rcp_f32_e32 v97, v97
	v_pk_mul_f32 v[50:51], v[50:51], v[142:143] op_sel_hi:[1,0]
	v_lshlrev_b32_e32 v139, 2, v139
	v_xor_b32_e32 v139, 0x80, v139
	v_pk_mul_f32 v[94:95], v[94:95], v[96:97]
	ds_bpermute_b32 v139, v139, v138
	v_pk_mul_f32 v[92:93], v[92:93], v[94:95]
	v_mul_f32_e32 v94, 0xbfb8aa3b, v86
	v_mul_f32_e32 v95, 0xbfb8aa3b, v87
	v_exp_f32_e32 v94, v94
	v_exp_f32_e32 v95, v95
	s_waitcnt lgkmcnt(0)
	v_add_f32_e32 v138, v138, v139
	v_fmamk_f32 v138, v138, 0x3a800000, v228
	v_add_f32_e32 v94, 1.0, v94
	v_add_f32_e32 v95, 1.0, v95
	v_rcp_f32_e32 v94, v94
	v_rcp_f32_e32 v95, v95
	v_rsq_f32_e32 v138, v138
	v_pk_mul_f32 v[52:53], v[52:53], v[142:143] op_sel_hi:[1,0]
	v_mbcnt_lo_u32_b32 v135, -1, v135
	v_pk_mul_f32 v[86:87], v[86:87], v[94:95]
	v_lshl_add_u64 v[94:95], v[162:163], 0, s[16:17]
	v_pk_mul_f32 v[86:87], v[82:83], v[86:87]
	v_pk_mul_f32 v[82:83], v[88:89], v[172:173] op_sel_hi:[1,0]
	v_pk_mul_f32 v[46:47], v[46:47], v[138:139] op_sel_hi:[1,0]
	v_mul_f32_e32 v88, 0xbfb8aa3b, v82
	v_mul_f32_e32 v89, 0xbfb8aa3b, v83
	v_exp_f32_e32 v88, v88
	v_exp_f32_e32 v89, v89
	v_pk_mul_f32 v[42:43], v[42:43], v[138:139] op_sel_hi:[1,0]
	v_pk_mul_f32 v[44:45], v[44:45], v[138:139] op_sel_hi:[1,0]
	v_add_f32_e32 v88, 1.0, v88
	v_add_f32_e32 v89, 1.0, v89
	v_rcp_f32_e32 v88, v88
	v_rcp_f32_e32 v89, v89
	v_pk_mul_f32 v[38:39], v[38:39], v[138:139] op_sel_hi:[1,0]
	v_pk_mul_f32 v[34:35], v[34:35], v[138:139] op_sel_hi:[1,0]
	v_mbcnt_hi_u32_b32 v135, -1, v135
	v_pk_mul_f32 v[82:83], v[82:83], v[88:89]
	v_lshlrev_b32_e32 v135, 2, v135
	v_pk_mul_f32 v[88:89], v[84:85], v[82:83]
	v_cvt_pk_bf16_f32 v84, v86, v87
	v_mad_u64_u32 v[86:87], s[18:19], v94, s89, v[130:131]
	v_cvt_pk_bf16_f32 v85, v88, v89
	v_mov_b32_e32 v88, v87
	v_mad_u64_u32 v[88:89], s[18:19], v95, s89, v[88:89]
	v_cvt_pk_bf16_f32 v82, v90, v91
	v_cvt_pk_bf16_f32 v83, v92, v93
	v_mov_b32_e32 v87, v88
	s_mov_b64 exec, s[98:99]
	global_store_dwordx4 v[86:87], v[82:85], off sc1
	s_mov_b64 exec, s[100:101]
	global_store_dwordx4 v[86:87], v[82:85], off
	s_mov_b64 exec, -1
	v_xor_b32_e32 v135, 0x80, v135
	ds_bpermute_b32 v135, v135, v134
	v_mul_f32_e32 v82, 0xbfb8aa3b, v78
	v_mul_f32_e32 v83, 0xbfb8aa3b, v79
	v_exp_f32_e32 v82, v82
	v_exp_f32_e32 v83, v83
	s_waitcnt lgkmcnt(0)
	v_add_f32_e32 v134, v134, v135
	v_fmamk_f32 v134, v134, 0x3a800000, v228
	v_add_f32_e32 v82, 1.0, v82
	v_add_f32_e32 v83, 1.0, v83
	v_rcp_f32_e32 v82, v82
	v_rcp_f32_e32 v83, v83
	v_rsq_f32_e32 v134, v134
	v_pk_mul_f32 v[36:37], v[36:37], v[138:139] op_sel_hi:[1,0]
	v_pk_mul_f32 v[14:15], v[14:15], v[132:133] op_sel_hi:[1,0]
	v_pk_mul_f32 v[78:79], v[78:79], v[82:83]
	v_pk_mul_f32 v[30:31], v[30:31], v[134:135] op_sel_hi:[1,0]
	v_pk_mul_f32 v[74:75], v[74:75], v[78:79]
	v_pk_mul_f32 v[78:79], v[80:81], v[146:147] op_sel_hi:[1,0]
	v_pk_mul_f32 v[26:27], v[26:27], v[134:135] op_sel_hi:[1,0]
	v_mul_f32_e32 v80, 0xbfb8aa3b, v78
	v_mul_f32_e32 v81, 0xbfb8aa3b, v79
	v_exp_f32_e32 v80, v80
	v_exp_f32_e32 v81, v81
	v_pk_mul_f32 v[28:29], v[28:29], v[134:135] op_sel_hi:[1,0]
	v_pk_mul_f32 v[22:23], v[22:23], v[134:135] op_sel_hi:[1,0]
	v_add_f32_e32 v80, 1.0, v80
	v_add_f32_e32 v81, 1.0, v81
	v_rcp_f32_e32 v80, v80
	v_rcp_f32_e32 v81, v81
	v_pk_mul_f32 v[18:19], v[18:19], v[134:135] op_sel_hi:[1,0]
	v_pk_mul_f32 v[20:21], v[20:21], v[134:135] op_sel_hi:[1,0]
	v_pk_mul_f32 v[10:11], v[10:11], v[132:133] op_sel_hi:[1,0]
	v_pk_mul_f32 v[78:79], v[78:79], v[80:81]
	v_pk_mul_f32 v[12:13], v[12:13], v[132:133] op_sel_hi:[1,0]
	v_pk_mul_f32 v[76:77], v[76:77], v[78:79]
	v_mul_f32_e32 v78, 0xbfb8aa3b, v70
	v_mul_f32_e32 v79, 0xbfb8aa3b, v71
	v_exp_f32_e32 v78, v78
	v_exp_f32_e32 v79, v79
	v_pk_mul_f32 v[6:7], v[6:7], v[132:133] op_sel_hi:[1,0]
	v_pk_mul_f32 v[2:3], v[2:3], v[132:133] op_sel_hi:[1,0]
	v_add_f32_e32 v78, 1.0, v78
	v_add_f32_e32 v79, 1.0, v79
	v_rcp_f32_e32 v78, v78
	v_rcp_f32_e32 v79, v79
	v_pk_mul_f32 v[4:5], v[4:5], v[132:133] op_sel_hi:[1,0]
	v_pk_mul_f32 v[70:71], v[70:71], v[78:79]
	s_nop 0
	v_pk_mul_f32 v[70:71], v[66:67], v[70:71]
	v_pk_mul_f32 v[66:67], v[72:73], v[146:147] op_sel_hi:[1,0]
	v_lshl_add_u64 v[78:79], v[164:165], 0, s[16:17]
	v_mul_f32_e32 v72, 0xbfb8aa3b, v66
	v_mul_f32_e32 v73, 0xbfb8aa3b, v67
	v_exp_f32_e32 v72, v72
	v_exp_f32_e32 v73, v73
	v_add_f32_e32 v72, 1.0, v72
	v_add_f32_e32 v73, 1.0, v73
	v_rcp_f32_e32 v72, v72
	v_rcp_f32_e32 v73, v73
	s_nop 0
	v_pk_mul_f32 v[66:67], v[66:67], v[72:73]
	s_nop 0
	v_pk_mul_f32 v[72:73], v[68:69], v[66:67]
	v_cvt_pk_bf16_f32 v68, v70, v71
	v_mad_u64_u32 v[70:71], s[16:17], v78, s89, v[130:131]
	v_cvt_pk_bf16_f32 v69, v72, v73
	v_mov_b32_e32 v72, v71
	v_mad_u64_u32 v[72:73], s[16:17], v79, s89, v[72:73]
	v_cvt_pk_bf16_f32 v66, v74, v75
	v_cvt_pk_bf16_f32 v67, v76, v77
	v_mov_b32_e32 v71, v72
	s_mov_b64 exec, s[98:99]
	global_store_dwordx4 v[70:71], v[66:69], off sc1
	s_mov_b64 exec, s[100:101]
	global_store_dwordx4 v[70:71], v[66:69], off
	s_mov_b64 exec, -1
	s_nop 1
	v_mul_f32_e32 v66, 0xbfb8aa3b, v62
	v_mul_f32_e32 v67, 0xbfb8aa3b, v63
	v_exp_f32_e32 v66, v66
	v_exp_f32_e32 v67, v67
	v_add_f32_e32 v66, 1.0, v66
	v_add_f32_e32 v67, 1.0, v67
	v_rcp_f32_e32 v66, v66
	v_rcp_f32_e32 v67, v67
	s_nop 0
	v_pk_mul_f32 v[62:63], v[62:63], v[66:67]
	s_nop 0
	v_pk_mul_f32 v[58:59], v[58:59], v[62:63]
	v_pk_mul_f32 v[62:63], v[64:65], v[142:143] op_sel_hi:[1,0]
	s_nop 0
	v_mul_f32_e32 v64, 0xbfb8aa3b, v62
	v_mul_f32_e32 v65, 0xbfb8aa3b, v63
	v_exp_f32_e32 v64, v64
	v_exp_f32_e32 v65, v65
	v_add_f32_e32 v64, 1.0, v64
	v_add_f32_e32 v65, 1.0, v65
	v_rcp_f32_e32 v64, v64
	v_rcp_f32_e32 v65, v65
	s_nop 0
	v_pk_mul_f32 v[62:63], v[62:63], v[64:65]
	s_nop 0
	v_pk_mul_f32 v[60:61], v[60:61], v[62:63]
	v_mul_f32_e32 v62, 0xbfb8aa3b, v54
	v_mul_f32_e32 v63, 0xbfb8aa3b, v55
	v_exp_f32_e32 v62, v62
	v_exp_f32_e32 v63, v63
	v_add_f32_e32 v62, 1.0, v62
	v_add_f32_e32 v63, 1.0, v63
	v_rcp_f32_e32 v62, v62
	v_rcp_f32_e32 v63, v63
	s_nop 0
	v_pk_mul_f32 v[54:55], v[54:55], v[62:63]
	s_nop 0
	v_pk_mul_f32 v[54:55], v[50:51], v[54:55]
	v_pk_mul_f32 v[50:51], v[56:57], v[142:143] op_sel_hi:[1,0]
	v_lshl_add_u64 v[62:63], v[170:171], 0, s[96:97]
	v_mul_f32_e32 v56, 0xbfb8aa3b, v50
	v_mul_f32_e32 v57, 0xbfb8aa3b, v51
	v_exp_f32_e32 v56, v56
	v_exp_f32_e32 v57, v57
	v_add_f32_e32 v56, 1.0, v56
	v_add_f32_e32 v57, 1.0, v57
	v_rcp_f32_e32 v56, v56
	v_rcp_f32_e32 v57, v57
	s_nop 0
	v_pk_mul_f32 v[50:51], v[50:51], v[56:57]
	s_nop 0
	v_pk_mul_f32 v[56:57], v[52:53], v[50:51]
	v_cvt_pk_bf16_f32 v52, v54, v55
	v_mad_u64_u32 v[54:55], s[16:17], v62, s89, v[130:131]
	v_cvt_pk_bf16_f32 v53, v56, v57
	v_mov_b32_e32 v56, v55
	v_mad_u64_u32 v[56:57], s[16:17], v63, s89, v[56:57]
	v_cvt_pk_bf16_f32 v50, v58, v59
	v_cvt_pk_bf16_f32 v51, v60, v61
	v_mov_b32_e32 v55, v56
	s_mov_b64 exec, s[98:99]
	global_store_dwordx4 v[54:55], v[50:53], off sc1
	s_mov_b64 exec, s[100:101]
	global_store_dwordx4 v[54:55], v[50:53], off
	s_mov_b64 exec, -1
	s_mov_b64 s[16:17], 0x90
	s_nop 0
	v_mul_f32_e32 v50, 0xbfb8aa3b, v46
	v_mul_f32_e32 v51, 0xbfb8aa3b, v47
	v_exp_f32_e32 v50, v50
	v_exp_f32_e32 v51, v51
	v_add_f32_e32 v50, 1.0, v50
	v_add_f32_e32 v51, 1.0, v51
	v_rcp_f32_e32 v50, v50
	v_rcp_f32_e32 v51, v51
	s_nop 0
	v_pk_mul_f32 v[46:47], v[46:47], v[50:51]
	s_nop 0
	v_pk_mul_f32 v[42:43], v[42:43], v[46:47]
	v_pk_mul_f32 v[46:47], v[48:49], v[138:139] op_sel_hi:[1,0]
	s_nop 0
	v_mul_f32_e32 v48, 0xbfb8aa3b, v46
	v_mul_f32_e32 v49, 0xbfb8aa3b, v47
	v_exp_f32_e32 v48, v48
	v_exp_f32_e32 v49, v49
	v_add_f32_e32 v48, 1.0, v48
	v_add_f32_e32 v49, 1.0, v49
	v_rcp_f32_e32 v48, v48
	v_rcp_f32_e32 v49, v49
	s_nop 0
	v_pk_mul_f32 v[46:47], v[46:47], v[48:49]
	s_nop 0
	v_pk_mul_f32 v[44:45], v[44:45], v[46:47]
	v_mul_f32_e32 v46, 0xbfb8aa3b, v38
	v_mul_f32_e32 v47, 0xbfb8aa3b, v39
	v_exp_f32_e32 v46, v46
	v_exp_f32_e32 v47, v47
	v_add_f32_e32 v46, 1.0, v46
	v_add_f32_e32 v47, 1.0, v47
	v_rcp_f32_e32 v46, v46
	v_rcp_f32_e32 v47, v47
	s_nop 0
	v_pk_mul_f32 v[38:39], v[38:39], v[46:47]
	s_nop 0
	v_pk_mul_f32 v[38:39], v[34:35], v[38:39]
	v_pk_mul_f32 v[34:35], v[40:41], v[138:139] op_sel_hi:[1,0]
	v_lshl_add_u64 v[46:47], v[170:171], 0, s[16:17]
	v_mul_f32_e32 v40, 0xbfb8aa3b, v34
	v_mul_f32_e32 v41, 0xbfb8aa3b, v35
	v_exp_f32_e32 v40, v40
	v_exp_f32_e32 v41, v41
	v_add_f32_e32 v40, 1.0, v40
	v_add_f32_e32 v41, 1.0, v41
	v_rcp_f32_e32 v40, v40
	v_rcp_f32_e32 v41, v41
	s_nop 0
	v_pk_mul_f32 v[34:35], v[34:35], v[40:41]
	s_nop 0
	v_pk_mul_f32 v[40:41], v[36:37], v[34:35]
	v_cvt_pk_bf16_f32 v36, v38, v39
	v_mad_u64_u32 v[38:39], s[16:17], v46, s89, v[130:131]
	v_cvt_pk_bf16_f32 v37, v40, v41
	v_mov_b32_e32 v40, v39
	v_mad_u64_u32 v[40:41], s[16:17], v47, s89, v[40:41]
	v_cvt_pk_bf16_f32 v34, v42, v43
	v_cvt_pk_bf16_f32 v35, v44, v45
	v_mov_b32_e32 v39, v40
	s_mov_b64 exec, s[98:99]
	global_store_dwordx4 v[38:39], v[34:37], off sc1
	s_mov_b64 exec, s[100:101]
	global_store_dwordx4 v[38:39], v[34:37], off
	s_mov_b64 exec, -1
	s_mov_b64 s[16:17], 0xa0
	s_nop 0
	v_mul_f32_e32 v34, 0xbfb8aa3b, v30
	v_mul_f32_e32 v35, 0xbfb8aa3b, v31
	v_exp_f32_e32 v34, v34
	v_exp_f32_e32 v35, v35
	v_add_f32_e32 v34, 1.0, v34
	v_add_f32_e32 v35, 1.0, v35
	v_rcp_f32_e32 v34, v34
	v_rcp_f32_e32 v35, v35
	s_nop 0
	v_pk_mul_f32 v[30:31], v[30:31], v[34:35]
	s_nop 0
	v_pk_mul_f32 v[26:27], v[26:27], v[30:31]
	v_pk_mul_f32 v[30:31], v[32:33], v[134:135] op_sel_hi:[1,0]
	s_nop 0
	v_mul_f32_e32 v32, 0xbfb8aa3b, v30
	v_mul_f32_e32 v33, 0xbfb8aa3b, v31
	v_exp_f32_e32 v32, v32
	v_exp_f32_e32 v33, v33
	v_add_f32_e32 v32, 1.0, v32
	v_add_f32_e32 v33, 1.0, v33
	v_rcp_f32_e32 v32, v32
	v_rcp_f32_e32 v33, v33
	s_nop 0
	v_pk_mul_f32 v[30:31], v[30:31], v[32:33]
	s_nop 0
	v_pk_mul_f32 v[28:29], v[28:29], v[30:31]
	v_mul_f32_e32 v30, 0xbfb8aa3b, v22
	v_mul_f32_e32 v31, 0xbfb8aa3b, v23
	v_exp_f32_e32 v30, v30
	v_exp_f32_e32 v31, v31
	v_add_f32_e32 v30, 1.0, v30
	v_add_f32_e32 v31, 1.0, v31
	v_rcp_f32_e32 v30, v30
	v_rcp_f32_e32 v31, v31
	s_nop 0
	v_pk_mul_f32 v[22:23], v[22:23], v[30:31]
	s_nop 0
	v_pk_mul_f32 v[22:23], v[18:19], v[22:23]
	v_pk_mul_f32 v[18:19], v[24:25], v[134:135] op_sel_hi:[1,0]
	v_lshl_add_u64 v[30:31], v[170:171], 0, s[16:17]
	v_mul_f32_e32 v24, 0xbfb8aa3b, v18
	v_mul_f32_e32 v25, 0xbfb8aa3b, v19
	v_exp_f32_e32 v24, v24
	v_exp_f32_e32 v25, v25
	v_add_f32_e32 v24, 1.0, v24
	v_add_f32_e32 v25, 1.0, v25
	v_rcp_f32_e32 v24, v24
	v_rcp_f32_e32 v25, v25
	s_nop 0
	v_pk_mul_f32 v[18:19], v[18:19], v[24:25]
	s_nop 0
	v_pk_mul_f32 v[24:25], v[20:21], v[18:19]
	v_cvt_pk_bf16_f32 v20, v22, v23
	v_mad_u64_u32 v[22:23], s[16:17], v30, s89, v[130:131]
	v_cvt_pk_bf16_f32 v21, v24, v25
	v_mov_b32_e32 v24, v23
	v_mad_u64_u32 v[24:25], s[16:17], v31, s89, v[24:25]
	v_cvt_pk_bf16_f32 v18, v26, v27
	v_cvt_pk_bf16_f32 v19, v28, v29
	v_mov_b32_e32 v23, v24
	s_mov_b64 exec, s[98:99]
	global_store_dwordx4 v[22:23], v[18:21], off sc1
	s_mov_b64 exec, s[100:101]
	global_store_dwordx4 v[22:23], v[18:21], off
	s_mov_b64 exec, -1
	s_mov_b64 s[16:17], 0xb0
	s_nop 0
	v_mul_f32_e32 v18, 0xbfb8aa3b, v14
	v_mul_f32_e32 v19, 0xbfb8aa3b, v15
	v_exp_f32_e32 v18, v18
	v_exp_f32_e32 v19, v19
	v_add_f32_e32 v18, 1.0, v18
	v_add_f32_e32 v19, 1.0, v19
	v_rcp_f32_e32 v18, v18
	v_rcp_f32_e32 v19, v19
	s_nop 0
	v_pk_mul_f32 v[14:15], v[14:15], v[18:19]
	s_nop 0
	v_pk_mul_f32 v[10:11], v[10:11], v[14:15]
	v_pk_mul_f32 v[14:15], v[16:17], v[132:133] op_sel_hi:[1,0]
	s_nop 0
	v_mul_f32_e32 v16, 0xbfb8aa3b, v14
	v_mul_f32_e32 v17, 0xbfb8aa3b, v15
	v_exp_f32_e32 v16, v16
	v_exp_f32_e32 v17, v17
	v_add_f32_e32 v16, 1.0, v16
	v_add_f32_e32 v17, 1.0, v17
	v_rcp_f32_e32 v16, v16
	v_rcp_f32_e32 v17, v17
	s_nop 0
	v_pk_mul_f32 v[14:15], v[14:15], v[16:17]
	s_nop 0
	v_pk_mul_f32 v[12:13], v[12:13], v[14:15]
	v_mul_f32_e32 v14, 0xbfb8aa3b, v6
	v_mul_f32_e32 v15, 0xbfb8aa3b, v7
	v_exp_f32_e32 v14, v14
	v_exp_f32_e32 v15, v15
	v_add_f32_e32 v14, 1.0, v14
	v_add_f32_e32 v15, 1.0, v15
	v_rcp_f32_e32 v14, v14
	v_rcp_f32_e32 v15, v15
	s_nop 0
	v_pk_mul_f32 v[6:7], v[6:7], v[14:15]
	s_nop 0
	v_pk_mul_f32 v[6:7], v[2:3], v[6:7]
	v_pk_mul_f32 v[2:3], v[8:9], v[132:133] op_sel_hi:[1,0]
	v_lshl_add_u64 v[14:15], v[170:171], 0, s[16:17]
	v_mul_f32_e32 v8, 0xbfb8aa3b, v2
	v_mul_f32_e32 v9, 0xbfb8aa3b, v3
	v_exp_f32_e32 v8, v8
	v_exp_f32_e32 v9, v9
	v_add_f32_e32 v8, 1.0, v8
	v_add_f32_e32 v9, 1.0, v9
	v_rcp_f32_e32 v8, v8
	v_rcp_f32_e32 v9, v9
	s_nop 0
	v_pk_mul_f32 v[2:3], v[2:3], v[8:9]
	s_nop 0
	v_pk_mul_f32 v[8:9], v[4:5], v[2:3]
	v_cvt_pk_bf16_f32 v4, v6, v7
	v_mad_u64_u32 v[6:7], s[16:17], v14, s89, v[130:131]
	v_cvt_pk_bf16_f32 v5, v8, v9
	v_mov_b32_e32 v8, v7
	v_mad_u64_u32 v[8:9], s[16:17], v15, s89, v[8:9]
	v_cvt_pk_bf16_f32 v2, v10, v11
	v_cvt_pk_bf16_f32 v3, v12, v13
	v_mov_b32_e32 v7, v8
	s_mov_b64 s[16:17], -1
	s_mov_b64 exec, s[98:99]
	global_store_dwordx4 v[6:7], v[2:5], off sc1
	s_mov_b64 exec, s[100:101]
	global_store_dwordx4 v[6:7], v[2:5], off
	s_mov_b64 exec, -1
	s_cbranch_vccnz .LBB0_399
	s_andn2_b64 vcc, exec, s[2:3]
	s_cbranch_vccnz .LBB0_398
	s_barrier
	s_branch .LBB0_398

.LBB0_2072:
	s_add_i32 s41, s41, 1
	s_mul_i32 s0, s41, s85
	s_mul_hi_u32 s1, s41, s84
	s_add_i32 s1, s1, s0
	s_mul_i32 s0, s41, s84
	s_add_u32 s16, s0, s28
	s_addc_u32 s17, s1, s34
	v_cmp_gt_i64_e32 vcc, s[16:17], v[238:239]
	v_mov_b64_e32 v[240:241], 0x100
	v_cmp_lt_i64_e64 s[0:1], s[16:17], v[234:235]
	s_mov_b64 s[100:101], s[0:1]
	s_not_b64 s[98:99], s[0:1]
	s_cbranch_vccnz .LBB0_2074
	s_ashr_i32 s12, s16, 31
	s_lshr_b32 s12, s12, 29
	s_add_i32 s12, s16, s12
	s_ashr_i32 s13, s12, 3
	s_and_b32 s12, s12, -8
	s_sub_i32 s12, s16, s12
	s_cmp_lt_i32 s12, 0
	s_cselect_b32 s14, s57, 0xb0
	s_mul_i32 s12, s12, s14
	s_add_i32 s12, s12, s13
	s_mul_hi_i32 s13, s12, 0x2e8ba2e9
	s_lshr_b32 s14, s13, 31
	s_ashr_i32 s13, s13, 5
	s_add_i32 s13, s13, s14
	s_lshl_b32 s14, s13, 3
	s_sub_i32 s15, 64, s14
	s_min_i32 s15, s15, 8
	s_abs_i32 s16, s15
	v_cvt_f32_u32_e32 v2, s16
	s_sub_i32 s18, 0, s16
	s_mulk_i32 s13, 0xb0
	s_sub_i32 s13, s12, s13
	v_rcp_iflag_f32_e32 v2, v2
	s_abs_i32 s12, s13
	s_xor_b32 s17, s13, s15
	s_ashr_i32 s17, s17, 31
	v_mul_f32_e32 v2, 0x4f7ffffe, v2
	v_cvt_u32_f32_e32 v2, v2
	s_nop 0
	v_readfirstlane_b32 s19, v2
	s_mul_i32 s18, s18, s19
	s_mul_hi_u32 s18, s19, s18
	s_add_i32 s19, s19, s18
	s_mul_hi_u32 s18, s12, s19
	s_mul_i32 s19, s18, s16
	s_sub_i32 s12, s12, s19
	s_add_i32 s26, s18, 1
	s_sub_i32 s19, s12, s16
	s_cmp_ge_u32 s12, s16
	s_cselect_b32 s18, s26, s18
	s_cselect_b32 s12, s19, s12
	s_add_i32 s19, s18, 1
	s_cmp_ge_u32 s12, s16
	s_cselect_b32 s12, s19, s18
	s_xor_b32 s12, s12, s17
	s_sub_i32 s12, s12, s17
	s_mul_i32 s15, s12, s15
	s_sub_i32 s13, s13, s15
	s_add_i32 s14, s14, s13

.LBB0_2078:
	s_mov_b32 s13, s33
	v_lshl_or_b32 v190, s21, 7, v175
	v_mov_b32_e32 v130, s13
	ds_read2_b32 v[130:131], v130 offset1:1
	s_ashr_i32 s21, s20, 31
	s_lshl_b64 s[20:21], s[20:21], 8
	v_lshl_add_u64 v[170:171], s[20:21], 0, v[158:159]
	v_lshlrev_b64 v[132:133], 6, v[170:171]
	s_waitcnt lgkmcnt(0)
	v_readfirstlane_b32 s13, v130
	v_readfirstlane_b32 s15, v131
	v_mov_b32_e32 v186, s13
	s_mov_b32 s13, s33
	v_mov_b32_e32 v187, s15
	v_mov_b32_e32 v130, s13
	ds_read2_b32 v[130:131], v130 offset1:1
	v_ashrrev_i32_e32 v191, 31, v190
	v_mov_b64_e32 v[226:227], v[240:241]
	s_waitcnt lgkmcnt(0)
	v_readfirstlane_b32 s22, v130
	v_readfirstlane_b32 s23, v131
	s_nop 1
	v_lshl_add_u64 v[130:131], s[22:23], 0, v[0:1]
	v_lshl_add_u64 v[130:131], v[130:131], 0, v[132:133]
	v_add_co_u32_e32 v134, vcc, s58, v130
	s_mov_b64 s[22:23], 0x10380000
	s_nop 0
	v_addc_co_u32_e32 v135, vcc, 0, v131, vcc
	v_lshl_add_u64 v[132:133], v[130:131], 0, s[22:23]
	global_load_dwordx4 v[176:179], v[134:135], off
	global_load_dwordx4 v[180:183], v[132:133], off offset:1024
	global_load_dwordx4 v[192:195], v[132:133], off offset:2048
	global_load_dwordx4 v[146:149], v[132:133], off offset:3072
	v_add_co_u32_e32 v130, vcc, s59, v130
	s_mov_b64 s[22:23], 0xaa00000
	s_nop 0
	v_addc_co_u32_e32 v131, vcc, 0, v131, vcc
	global_load_dwordx4 v[142:145], v[130:131], off
	global_load_dwordx4 v[138:141], v[130:131], off offset:1024
	global_load_dwordx4 v[134:137], v[130:131], off offset:2048
	s_nop 0
	global_load_dwordx4 v[130:133], v[130:131], off offset:3072
	s_andn2_b64 vcc, exec, s[0:1]
	s_waitcnt vmcnt(0)
	v_mov_b32_e32 v188, v177
	v_mov_b32_e32 v189, v178
	v_mov_b32_e32 v177, v179
	v_pk_add_f32 v[176:177], v[188:189], v[176:177]
	s_nop 0
	v_add_f32_e32 v172, v176, v177
	v_mov_b32_e32 v174, v172
	s_nop 1
	v_permlane16_swap_b32_e32 v174, v172
	v_mov_b32_e32 v176, v181
	v_mov_b32_e32 v177, v182
	v_mov_b32_e32 v181, v183
	v_pk_add_f32 v[176:177], v[176:177], v[180:181]
	s_waitcnt lgkmcnt(0)
	v_add_f32_e32 v172, v172, v174
	s_nop 0
	v_mov_b32_e32 v174, v172
	s_nop 1
	v_permlane32_swap_b32_e32 v174, v172
	s_waitcnt lgkmcnt(0)
	v_add_f32_e32 v172, v172, v174
	v_fmamk_f32 v172, v172, 0x3a800000, v228
	v_rsq_f32_e32 v188, v172
	v_add_f32_e32 v172, v176, v177
	v_mov_b32_e32 v174, v172
	s_nop 1
	v_permlane16_swap_b32_e32 v174, v172
	v_mov_b32_e32 v176, v193
	v_mov_b32_e32 v177, v194
	v_mov_b32_e32 v193, v195
	v_pk_add_f32 v[176:177], v[176:177], v[192:193]
	s_waitcnt lgkmcnt(0)
	v_add_f32_e32 v172, v172, v174
	v_pk_mul_f32 v[126:127], v[126:127], v[188:189] op_sel_hi:[1,0]
	v_mov_b32_e32 v174, v172
	s_nop 1
	v_permlane32_swap_b32_e32 v174, v172
	v_pk_mul_f32 v[122:123], v[122:123], v[188:189] op_sel_hi:[1,0]
	v_pk_mul_f32 v[124:125], v[124:125], v[188:189] op_sel_hi:[1,0]
	v_pk_mul_f32 v[118:119], v[118:119], v[188:189] op_sel_hi:[1,0]
	v_pk_mul_f32 v[114:115], v[114:115], v[188:189] op_sel_hi:[1,0]
	s_waitcnt lgkmcnt(0)
	v_add_f32_e32 v172, v172, v174
	v_fmamk_f32 v172, v172, 0x3a800000, v228
	v_rsq_f32_e32 v174, v172
	v_add_f32_e32 v172, v176, v177
	v_mov_b32_e32 v177, v148
	v_mov_b32_e32 v176, v172
	s_nop 1
	v_permlane16_swap_b32_e32 v176, v172
	v_mov_b32_e32 v148, v143
	v_mov_b32_e32 v143, v145
	v_mov_b32_e32 v145, v140
	v_mov_b32_e32 v140, v135
	s_waitcnt lgkmcnt(0)
	v_add_f32_e32 v172, v172, v176
	v_mov_b32_e32 v135, v137
	v_mov_b32_e32 v176, v172
	s_nop 1
	v_permlane32_swap_b32_e32 v176, v172
	v_mov_b32_e32 v137, v132
	v_pk_mul_f32 v[116:117], v[116:117], v[188:189] op_sel_hi:[1,0]
	v_pk_mul_f32 v[110:111], v[110:111], v[174:175] op_sel_hi:[1,0]
	v_pk_mul_f32 v[106:107], v[106:107], v[174:175] op_sel_hi:[1,0]
	s_waitcnt lgkmcnt(0)
	v_add_f32_e32 v172, v172, v176
	v_mov_b32_e32 v176, v147
	v_mov_b32_e32 v147, v149
	v_pk_add_f32 v[146:147], v[176:177], v[146:147]
	v_mov_b32_e32 v149, v144
	v_add_f32_e32 v146, v146, v147
	v_pk_add_f32 v[142:143], v[148:149], v[142:143]
	v_mov_b32_e32 v147, v146
	s_nop 1
	v_permlane16_swap_b32_e32 v147, v146
	v_add_f32_e32 v142, v142, v143
	v_mov_b32_e32 v144, v139
	v_mov_b32_e32 v139, v141
	s_waitcnt lgkmcnt(0)
	v_add_f32_e32 v146, v146, v147
	v_mov_b32_e32 v147, v1
	v_mov_b32_e32 v141, v136
	v_mov_b32_e32 v143, v142
	s_nop 1
	v_permlane16_swap_b32_e32 v143, v142
	v_mov_b32_e32 v136, v131
	v_mov_b32_e32 v131, v133
	v_mul_f32_e32 v133, 0xbfb8aa3b, v126
	v_exp_f32_e32 v133, v133
	v_pk_add_f32 v[138:139], v[144:145], v[138:139]
	s_waitcnt lgkmcnt(0)
	v_add_f32_e32 v142, v142, v143
	v_mov_b32_e32 v143, v1
	v_add_f32_e32 v138, v138, v139
	v_add_f32_e32 v133, 1.0, v133
	v_pk_add_f32 v[130:131], v[136:137], v[130:131]
	v_rcp_f32_e32 v136, v133
	v_mul_f32_e32 v133, 0xbfb8aa3b, v127
	v_exp_f32_e32 v133, v133
	v_mov_b32_e32 v139, v138
	s_nop 1
	v_permlane16_swap_b32_e32 v139, v138
	v_add_f32_e32 v133, 1.0, v133
	v_rcp_f32_e32 v137, v133
	v_pk_add_f32 v[134:135], v[140:141], v[134:135]
	v_add_f32_e32 v130, v130, v131
	s_waitcnt lgkmcnt(0)
	v_add_f32_e32 v138, v138, v139
	v_mov_b32_e32 v139, v1
	v_add_f32_e32 v134, v134, v135
	v_pk_mul_f32 v[126:127], v[126:127], v[136:137]
	v_pk_mul_f32 v[122:123], v[122:123], v[126:127]
	v_pk_mul_f32 v[126:127], v[128:129], v[188:189] op_sel_hi:[1,0]
	v_mul_f32_e32 v128, 0xbfb8aa3b, v126
	v_mul_f32_e32 v129, 0xbfb8aa3b, v127
	v_exp_f32_e32 v128, v128
	v_exp_f32_e32 v129, v129
	v_mov_b32_e32 v135, v134
	s_nop 1
	v_permlane16_swap_b32_e32 v135, v134
	v_add_f32_e32 v128, 1.0, v128
	v_add_f32_e32 v129, 1.0, v129
	v_rcp_f32_e32 v128, v128
	v_rcp_f32_e32 v129, v129
	s_waitcnt lgkmcnt(0)
	v_add_f32_e32 v134, v134, v135
	v_mov_b32_e32 v135, v1
	v_pk_mul_f32 v[126:127], v[126:127], v[128:129]
	v_pk_mul_f32 v[124:125], v[124:125], v[126:127]
	v_mul_f32_e32 v126, 0xbfb8aa3b, v118
	v_mul_f32_e32 v127, 0xbfb8aa3b, v119
	v_exp_f32_e32 v126, v126
	v_exp_f32_e32 v127, v127
	v_mov_b32_e32 v131, v130
	s_nop 1
	v_permlane16_swap_b32_e32 v131, v130
	v_add_f32_e32 v126, 1.0, v126
	v_add_f32_e32 v127, 1.0, v127
	v_rcp_f32_e32 v126, v126
	v_rcp_f32_e32 v127, v127
	s_waitcnt lgkmcnt(0)
	v_add_f32_e32 v130, v130, v131
	v_pk_mul_f32 v[118:119], v[118:119], v[126:127]
	v_pk_mul_f32 v[118:119], v[114:115], v[118:119]
	v_pk_mul_f32 v[114:115], v[120:121], v[188:189] op_sel_hi:[1,0]
	v_mul_f32_e32 v120, 0xbfb8aa3b, v114
	v_mul_f32_e32 v121, 0xbfb8aa3b, v115
	v_exp_f32_e32 v120, v120
	v_exp_f32_e32 v121, v121
	v_mov_b32_e32 v131, v130
	s_nop 1
	v_permlane32_swap_b32_e32 v131, v130
	v_pk_mul_f32 v[108:109], v[108:109], v[174:175] op_sel_hi:[1,0]
	v_add_f32_e32 v120, 1.0, v120
	v_add_f32_e32 v121, 1.0, v121
	v_rcp_f32_e32 v120, v120
	v_rcp_f32_e32 v121, v121
	s_waitcnt lgkmcnt(0)
	v_add_f32_e32 v130, v130, v131
	v_fmamk_f32 v130, v130, 0x3a800000, v228
	v_rsq_f32_e32 v132, v130
	v_lshl_add_u64 v[130:131], v[190:191], 1, v[186:187]
	v_lshl_add_u64 v[130:131], v[130:131], 0, s[22:23]
	v_pk_mul_f32 v[114:115], v[114:115], v[120:121]
	v_pk_mul_f32 v[102:103], v[102:103], v[174:175] op_sel_hi:[1,0]
	v_pk_mul_f32 v[120:121], v[116:117], v[114:115]
	v_cvt_pk_bf16_f32 v116, v118, v119
	v_mad_u64_u32 v[118:119], s[22:23], v170, s89, v[130:131]
	v_cvt_pk_bf16_f32 v117, v120, v121
	v_mov_b32_e32 v120, v119
	v_mad_u64_u32 v[120:121], s[22:23], v171, s89, v[120:121]
	v_cvt_pk_bf16_f32 v114, v122, v123
	v_cvt_pk_bf16_f32 v115, v124, v125
	v_mov_b32_e32 v119, v120
	s_mov_b64 exec, s[98:99]
	global_store_dwordx4 v[118:119], v[114:117], off sc1
	s_mov_b64 exec, s[100:101]
	global_store_dwordx4 v[118:119], v[114:117], off
	s_mov_b64 exec, -1
	v_pk_mul_f32 v[98:99], v[98:99], v[174:175] op_sel_hi:[1,0]
	v_fmamk_f32 v172, v172, 0x3a800000, v228
	v_mul_f32_e32 v114, 0xbfb8aa3b, v110
	v_mul_f32_e32 v115, 0xbfb8aa3b, v111
	v_exp_f32_e32 v114, v114
	v_exp_f32_e32 v115, v115
	v_rsq_f32_e32 v172, v172
	v_pk_mul_f32 v[100:101], v[100:101], v[174:175] op_sel_hi:[1,0]
	v_add_f32_e32 v114, 1.0, v114
	v_add_f32_e32 v115, 1.0, v115
	v_rcp_f32_e32 v114, v114
	v_rcp_f32_e32 v115, v115
	v_pk_mul_f32 v[94:95], v[94:95], v[172:173] op_sel_hi:[1,0]
	v_pk_mul_f32 v[90:91], v[90:91], v[172:173] op_sel_hi:[1,0]
	v_pk_mul_f32 v[92:93], v[92:93], v[172:173] op_sel_hi:[1,0]
	v_pk_mul_f32 v[110:111], v[110:111], v[114:115]
	v_pk_mul_f32 v[86:87], v[86:87], v[172:173] op_sel_hi:[1,0]
	v_pk_mul_f32 v[106:107], v[106:107], v[110:111]
	v_pk_mul_f32 v[110:111], v[112:113], v[174:175] op_sel_hi:[1,0]
	v_pk_mul_f32 v[82:83], v[82:83], v[172:173] op_sel_hi:[1,0]
	v_mul_f32_e32 v112, 0xbfb8aa3b, v110
	v_mul_f32_e32 v113, 0xbfb8aa3b, v111
	v_exp_f32_e32 v112, v112
	v_exp_f32_e32 v113, v113
	v_mbcnt_lo_u32_b32 v147, -1, v147
	v_mbcnt_hi_u32_b32 v147, -1, v147
	v_add_f32_e32 v112, 1.0, v112
	v_add_f32_e32 v113, 1.0, v113
	v_rcp_f32_e32 v112, v112
	v_rcp_f32_e32 v113, v113
	v_lshlrev_b32_e32 v147, 2, v147
	v_xor_b32_e32 v147, 0x80, v147
	ds_bpermute_b32 v147, v147, v146
	v_pk_mul_f32 v[110:111], v[110:111], v[112:113]
	v_pk_mul_f32 v[84:85], v[84:85], v[172:173] op_sel_hi:[1,0]
	v_pk_mul_f32 v[108:109], v[108:109], v[110:111]
	v_mul_f32_e32 v110, 0xbfb8aa3b, v102
	v_mul_f32_e32 v111, 0xbfb8aa3b, v103
	v_exp_f32_e32 v110, v110
	v_exp_f32_e32 v111, v111
	s_waitcnt lgkmcnt(0)
	v_add_f32_e32 v146, v146, v147
	v_fmamk_f32 v146, v146, 0x3a800000, v228
	v_add_f32_e32 v110, 1.0, v110
	v_add_f32_e32 v111, 1.0, v111
	v_rcp_f32_e32 v110, v110
	v_rcp_f32_e32 v111, v111
	v_rsq_f32_e32 v146, v146
	v_mbcnt_lo_u32_b32 v143, -1, v143
	v_mbcnt_hi_u32_b32 v143, -1, v143
	v_pk_mul_f32 v[102:103], v[102:103], v[110:111]
	v_lshl_add_u64 v[110:111], v[160:161], 0, s[20:21]
	v_pk_mul_f32 v[102:103], v[98:99], v[102:103]
	v_pk_mul_f32 v[98:99], v[104:105], v[174:175] op_sel_hi:[1,0]
	v_pk_mul_f32 v[78:79], v[78:79], v[146:147] op_sel_hi:[1,0]
	v_mul_f32_e32 v104, 0xbfb8aa3b, v98
	v_mul_f32_e32 v105, 0xbfb8aa3b, v99
	v_exp_f32_e32 v104, v104
	v_exp_f32_e32 v105, v105
	v_pk_mul_f32 v[74:75], v[74:75], v[146:147] op_sel_hi:[1,0]
	v_pk_mul_f32 v[76:77], v[76:77], v[146:147] op_sel_hi:[1,0]
	v_add_f32_e32 v104, 1.0, v104
	v_add_f32_e32 v105, 1.0, v105
	v_rcp_f32_e32 v104, v104
	v_rcp_f32_e32 v105, v105
	v_pk_mul_f32 v[70:71], v[70:71], v[146:147] op_sel_hi:[1,0]
	v_pk_mul_f32 v[66:67], v[66:67], v[146:147] op_sel_hi:[1,0]
	v_lshlrev_b32_e32 v143, 2, v143
	v_pk_mul_f32 v[98:99], v[98:99], v[104:105]
	v_xor_b32_e32 v143, 0x80, v143
	v_pk_mul_f32 v[104:105], v[100:101], v[98:99]
	v_cvt_pk_bf16_f32 v100, v102, v103
	v_mad_u64_u32 v[102:103], s[22:23], v110, s89, v[130:131]
	v_cvt_pk_bf16_f32 v101, v104, v105
	v_mov_b32_e32 v104, v103
	v_mad_u64_u32 v[104:105], s[22:23], v111, s89, v[104:105]
	v_cvt_pk_bf16_f32 v98, v106, v107
	v_cvt_pk_bf16_f32 v99, v108, v109
	v_mov_b32_e32 v103, v104
	s_mov_b64 exec, s[98:99]
	global_store_dwordx4 v[102:103], v[98:101], off sc1
	s_mov_b64 exec, s[100:101]
	global_store_dwordx4 v[102:103], v[98:101], off
	s_mov_b64 exec, -1
	ds_bpermute_b32 v143, v143, v142
	v_pk_mul_f32 v[68:69], v[68:69], v[146:147] op_sel_hi:[1,0]
	v_mul_f32_e32 v98, 0xbfb8aa3b, v94
	v_mul_f32_e32 v99, 0xbfb8aa3b, v95
	v_exp_f32_e32 v98, v98
	v_exp_f32_e32 v99, v99
	s_waitcnt lgkmcnt(0)
	v_add_f32_e32 v142, v142, v143
	v_fmamk_f32 v142, v142, 0x3a800000, v228
	v_add_f32_e32 v98, 1.0, v98
	v_add_f32_e32 v99, 1.0, v99
	v_rcp_f32_e32 v98, v98
	v_rcp_f32_e32 v99, v99
	v_rsq_f32_e32 v142, v142
	v_mbcnt_lo_u32_b32 v139, -1, v139
	v_mbcnt_hi_u32_b32 v139, -1, v139
	v_pk_mul_f32 v[94:95], v[94:95], v[98:99]
	v_pk_mul_f32 v[62:63], v[62:63], v[142:143] op_sel_hi:[1,0]
	v_pk_mul_f32 v[90:91], v[90:91], v[94:95]
	v_pk_mul_f32 v[94:95], v[96:97], v[172:173] op_sel_hi:[1,0]
	v_pk_mul_f32 v[58:59], v[58:59], v[142:143] op_sel_hi:[1,0]
	v_mul_f32_e32 v96, 0xbfb8aa3b, v94
	v_mul_f32_e32 v97, 0xbfb8aa3b, v95
	v_exp_f32_e32 v96, v96
	v_exp_f32_e32 v97, v97
	v_pk_mul_f32 v[60:61], v[60:61], v[142:143] op_sel_hi:[1,0]
	v_pk_mul_f32 v[54:55], v[54:55], v[142:143] op_sel_hi:[1,0]
	v_add_f32_e32 v96, 1.0, v96
	v_add_f32_e32 v97, 1.0, v97
	v_rcp_f32_e32 v96, v96
	v_rcp_f32_e32 v97, v97
	v_pk_mul_f32 v[50:51], v[50:51], v[142:143] op_sel_hi:[1,0]
	v_lshlrev_b32_e32 v139, 2, v139
	v_xor_b32_e32 v139, 0x80, v139
	v_pk_mul_f32 v[94:95], v[94:95], v[96:97]
	ds_bpermute_b32 v139, v139, v138
	v_pk_mul_f32 v[92:93], v[92:93], v[94:95]
	v_mul_f32_e32 v94, 0xbfb8aa3b, v86
	v_mul_f32_e32 v95, 0xbfb8aa3b, v87
	v_exp_f32_e32 v94, v94
	v_exp_f32_e32 v95, v95
	s_waitcnt lgkmcnt(0)
	v_add_f32_e32 v138, v138, v139
	v_fmamk_f32 v138, v138, 0x3a800000, v228
	v_add_f32_e32 v94, 1.0, v94
	v_add_f32_e32 v95, 1.0, v95
	v_rcp_f32_e32 v94, v94
	v_rcp_f32_e32 v95, v95
	v_rsq_f32_e32 v138, v138
	v_pk_mul_f32 v[52:53], v[52:53], v[142:143] op_sel_hi:[1,0]
	v_mbcnt_lo_u32_b32 v135, -1, v135
	v_pk_mul_f32 v[86:87], v[86:87], v[94:95]
	v_lshl_add_u64 v[94:95], v[162:163], 0, s[20:21]
	v_pk_mul_f32 v[86:87], v[82:83], v[86:87]
	v_pk_mul_f32 v[82:83], v[88:89], v[172:173] op_sel_hi:[1,0]
	v_pk_mul_f32 v[46:47], v[46:47], v[138:139] op_sel_hi:[1,0]
	v_mul_f32_e32 v88, 0xbfb8aa3b, v82
	v_mul_f32_e32 v89, 0xbfb8aa3b, v83
	v_exp_f32_e32 v88, v88
	v_exp_f32_e32 v89, v89
	v_pk_mul_f32 v[42:43], v[42:43], v[138:139] op_sel_hi:[1,0]
	v_pk_mul_f32 v[44:45], v[44:45], v[138:139] op_sel_hi:[1,0]
	v_add_f32_e32 v88, 1.0, v88
	v_add_f32_e32 v89, 1.0, v89
	v_rcp_f32_e32 v88, v88
	v_rcp_f32_e32 v89, v89
	v_pk_mul_f32 v[38:39], v[38:39], v[138:139] op_sel_hi:[1,0]
	v_pk_mul_f32 v[34:35], v[34:35], v[138:139] op_sel_hi:[1,0]
	v_mbcnt_hi_u32_b32 v135, -1, v135
	v_pk_mul_f32 v[82:83], v[82:83], v[88:89]
	v_lshlrev_b32_e32 v135, 2, v135
	v_pk_mul_f32 v[88:89], v[84:85], v[82:83]
	v_cvt_pk_bf16_f32 v84, v86, v87
	v_mad_u64_u32 v[86:87], s[22:23], v94, s89, v[130:131]
	v_cvt_pk_bf16_f32 v85, v88, v89
	v_mov_b32_e32 v88, v87
	v_mad_u64_u32 v[88:89], s[22:23], v95, s89, v[88:89]
	v_cvt_pk_bf16_f32 v82, v90, v91
	v_cvt_pk_bf16_f32 v83, v92, v93
	v_mov_b32_e32 v87, v88
	s_mov_b64 exec, s[98:99]
	global_store_dwordx4 v[86:87], v[82:85], off sc1
	s_mov_b64 exec, s[100:101]
	global_store_dwordx4 v[86:87], v[82:85], off
	s_mov_b64 exec, -1
	v_xor_b32_e32 v135, 0x80, v135
	ds_bpermute_b32 v135, v135, v134
	v_mul_f32_e32 v82, 0xbfb8aa3b, v78
	v_mul_f32_e32 v83, 0xbfb8aa3b, v79
	v_exp_f32_e32 v82, v82
	v_exp_f32_e32 v83, v83
	s_waitcnt lgkmcnt(0)
	v_add_f32_e32 v134, v134, v135
	v_fmamk_f32 v134, v134, 0x3a800000, v228
	v_add_f32_e32 v82, 1.0, v82
	v_add_f32_e32 v83, 1.0, v83
	v_rcp_f32_e32 v82, v82
	v_rcp_f32_e32 v83, v83
	v_rsq_f32_e32 v134, v134
	v_pk_mul_f32 v[36:37], v[36:37], v[138:139] op_sel_hi:[1,0]
	v_pk_mul_f32 v[14:15], v[14:15], v[132:133] op_sel_hi:[1,0]
	v_pk_mul_f32 v[78:79], v[78:79], v[82:83]
	v_pk_mul_f32 v[30:31], v[30:31], v[134:135] op_sel_hi:[1,0]
	v_pk_mul_f32 v[74:75], v[74:75], v[78:79]
	v_pk_mul_f32 v[78:79], v[80:81], v[146:147] op_sel_hi:[1,0]
	v_pk_mul_f32 v[26:27], v[26:27], v[134:135] op_sel_hi:[1,0]
	v_mul_f32_e32 v80, 0xbfb8aa3b, v78
	v_mul_f32_e32 v81, 0xbfb8aa3b, v79
	v_exp_f32_e32 v80, v80
	v_exp_f32_e32 v81, v81
	v_pk_mul_f32 v[28:29], v[28:29], v[134:135] op_sel_hi:[1,0]
	v_pk_mul_f32 v[22:23], v[22:23], v[134:135] op_sel_hi:[1,0]
	v_add_f32_e32 v80, 1.0, v80
	v_add_f32_e32 v81, 1.0, v81
	v_rcp_f32_e32 v80, v80
	v_rcp_f32_e32 v81, v81
	v_pk_mul_f32 v[18:19], v[18:19], v[134:135] op_sel_hi:[1,0]
	v_pk_mul_f32 v[20:21], v[20:21], v[134:135] op_sel_hi:[1,0]
	v_pk_mul_f32 v[10:11], v[10:11], v[132:133] op_sel_hi:[1,0]
	v_pk_mul_f32 v[78:79], v[78:79], v[80:81]
	v_pk_mul_f32 v[12:13], v[12:13], v[132:133] op_sel_hi:[1,0]
	v_pk_mul_f32 v[76:77], v[76:77], v[78:79]
	v_mul_f32_e32 v78, 0xbfb8aa3b, v70
	v_mul_f32_e32 v79, 0xbfb8aa3b, v71
	v_exp_f32_e32 v78, v78
	v_exp_f32_e32 v79, v79
	v_pk_mul_f32 v[6:7], v[6:7], v[132:133] op_sel_hi:[1,0]
	v_pk_mul_f32 v[2:3], v[2:3], v[132:133] op_sel_hi:[1,0]
	v_add_f32_e32 v78, 1.0, v78
	v_add_f32_e32 v79, 1.0, v79
	v_rcp_f32_e32 v78, v78
	v_rcp_f32_e32 v79, v79
	v_pk_mul_f32 v[4:5], v[4:5], v[132:133] op_sel_hi:[1,0]
	v_pk_mul_f32 v[70:71], v[70:71], v[78:79]
	s_nop 0
	v_pk_mul_f32 v[70:71], v[66:67], v[70:71]
	v_pk_mul_f32 v[66:67], v[72:73], v[146:147] op_sel_hi:[1,0]
	v_lshl_add_u64 v[78:79], v[164:165], 0, s[20:21]
	v_mul_f32_e32 v72, 0xbfb8aa3b, v66
	v_mul_f32_e32 v73, 0xbfb8aa3b, v67
	v_exp_f32_e32 v72, v72
	v_exp_f32_e32 v73, v73
	v_add_f32_e32 v72, 1.0, v72
	v_add_f32_e32 v73, 1.0, v73
	v_rcp_f32_e32 v72, v72
	v_rcp_f32_e32 v73, v73
	s_nop 0
	v_pk_mul_f32 v[66:67], v[66:67], v[72:73]
	s_nop 0
	v_pk_mul_f32 v[72:73], v[68:69], v[66:67]
	v_cvt_pk_bf16_f32 v68, v70, v71
	v_mad_u64_u32 v[70:71], s[20:21], v78, s89, v[130:131]
	v_cvt_pk_bf16_f32 v69, v72, v73
	v_mov_b32_e32 v72, v71
	v_mad_u64_u32 v[72:73], s[20:21], v79, s89, v[72:73]
	v_cvt_pk_bf16_f32 v66, v74, v75
	v_cvt_pk_bf16_f32 v67, v76, v77
	v_mov_b32_e32 v71, v72
	s_mov_b64 exec, s[98:99]
	global_store_dwordx4 v[70:71], v[66:69], off sc1
	s_mov_b64 exec, s[100:101]
	global_store_dwordx4 v[70:71], v[66:69], off
	s_mov_b64 exec, -1
	s_nop 1
	v_mul_f32_e32 v66, 0xbfb8aa3b, v62
	v_mul_f32_e32 v67, 0xbfb8aa3b, v63
	v_exp_f32_e32 v66, v66
	v_exp_f32_e32 v67, v67
	v_add_f32_e32 v66, 1.0, v66
	v_add_f32_e32 v67, 1.0, v67
	v_rcp_f32_e32 v66, v66
	v_rcp_f32_e32 v67, v67
	s_nop 0
	v_pk_mul_f32 v[62:63], v[62:63], v[66:67]
	s_nop 0
	v_pk_mul_f32 v[58:59], v[58:59], v[62:63]
	v_pk_mul_f32 v[62:63], v[64:65], v[142:143] op_sel_hi:[1,0]
	s_nop 0
	v_mul_f32_e32 v64, 0xbfb8aa3b, v62
	v_mul_f32_e32 v65, 0xbfb8aa3b, v63
	v_exp_f32_e32 v64, v64
	v_exp_f32_e32 v65, v65
	v_add_f32_e32 v64, 1.0, v64
	v_add_f32_e32 v65, 1.0, v65
	v_rcp_f32_e32 v64, v64
	v_rcp_f32_e32 v65, v65
	s_nop 0
	v_pk_mul_f32 v[62:63], v[62:63], v[64:65]
	s_nop 0
	v_pk_mul_f32 v[60:61], v[60:61], v[62:63]
	v_mul_f32_e32 v62, 0xbfb8aa3b, v54
	v_mul_f32_e32 v63, 0xbfb8aa3b, v55
	v_exp_f32_e32 v62, v62
	v_exp_f32_e32 v63, v63
	v_add_f32_e32 v62, 1.0, v62
	v_add_f32_e32 v63, 1.0, v63
	v_rcp_f32_e32 v62, v62
	v_rcp_f32_e32 v63, v63
	s_nop 0
	v_pk_mul_f32 v[54:55], v[54:55], v[62:63]
	s_nop 0
	v_pk_mul_f32 v[54:55], v[50:51], v[54:55]
	v_pk_mul_f32 v[50:51], v[56:57], v[142:143] op_sel_hi:[1,0]
	v_lshl_add_u64 v[62:63], v[170:171], 0, s[96:97]
	v_mul_f32_e32 v56, 0xbfb8aa3b, v50
	v_mul_f32_e32 v57, 0xbfb8aa3b, v51
	v_exp_f32_e32 v56, v56
	v_exp_f32_e32 v57, v57
	v_add_f32_e32 v56, 1.0, v56
	v_add_f32_e32 v57, 1.0, v57
	v_rcp_f32_e32 v56, v56
	v_rcp_f32_e32 v57, v57
	s_nop 0
	v_pk_mul_f32 v[50:51], v[50:51], v[56:57]
	s_nop 0
	v_pk_mul_f32 v[56:57], v[52:53], v[50:51]
	v_cvt_pk_bf16_f32 v52, v54, v55
	v_mad_u64_u32 v[54:55], s[20:21], v62, s89, v[130:131]
	v_cvt_pk_bf16_f32 v53, v56, v57
	v_mov_b32_e32 v56, v55
	v_mad_u64_u32 v[56:57], s[20:21], v63, s89, v[56:57]
	v_cvt_pk_bf16_f32 v50, v58, v59
	v_cvt_pk_bf16_f32 v51, v60, v61
	v_mov_b32_e32 v55, v56
	s_mov_b64 exec, s[98:99]
	global_store_dwordx4 v[54:55], v[50:53], off sc1
	s_mov_b64 exec, s[100:101]
	global_store_dwordx4 v[54:55], v[50:53], off
	s_mov_b64 exec, -1
	s_mov_b64 s[20:21], 0x90
	s_nop 0
	v_mul_f32_e32 v50, 0xbfb8aa3b, v46
	v_mul_f32_e32 v51, 0xbfb8aa3b, v47
	v_exp_f32_e32 v50, v50
	v_exp_f32_e32 v51, v51
	v_add_f32_e32 v50, 1.0, v50
	v_add_f32_e32 v51, 1.0, v51
	v_rcp_f32_e32 v50, v50
	v_rcp_f32_e32 v51, v51
	s_nop 0
	v_pk_mul_f32 v[46:47], v[46:47], v[50:51]
	s_nop 0
	v_pk_mul_f32 v[42:43], v[42:43], v[46:47]
	v_pk_mul_f32 v[46:47], v[48:49], v[138:139] op_sel_hi:[1,0]
	s_nop 0
	v_mul_f32_e32 v48, 0xbfb8aa3b, v46
	v_mul_f32_e32 v49, 0xbfb8aa3b, v47
	v_exp_f32_e32 v48, v48
	v_exp_f32_e32 v49, v49
	v_add_f32_e32 v48, 1.0, v48
	v_add_f32_e32 v49, 1.0, v49
	v_rcp_f32_e32 v48, v48
	v_rcp_f32_e32 v49, v49
	s_nop 0
	v_pk_mul_f32 v[46:47], v[46:47], v[48:49]
	s_nop 0
	v_pk_mul_f32 v[44:45], v[44:45], v[46:47]
	v_mul_f32_e32 v46, 0xbfb8aa3b, v38
	v_mul_f32_e32 v47, 0xbfb8aa3b, v39
	v_exp_f32_e32 v46, v46
	v_exp_f32_e32 v47, v47
	v_add_f32_e32 v46, 1.0, v46
	v_add_f32_e32 v47, 1.0, v47
	v_rcp_f32_e32 v46, v46
	v_rcp_f32_e32 v47, v47
	s_nop 0
	v_pk_mul_f32 v[38:39], v[38:39], v[46:47]
	s_nop 0
	v_pk_mul_f32 v[38:39], v[34:35], v[38:39]
	v_pk_mul_f32 v[34:35], v[40:41], v[138:139] op_sel_hi:[1,0]
	v_lshl_add_u64 v[46:47], v[170:171], 0, s[20:21]
	v_mul_f32_e32 v40, 0xbfb8aa3b, v34
	v_mul_f32_e32 v41, 0xbfb8aa3b, v35
	v_exp_f32_e32 v40, v40
	v_exp_f32_e32 v41, v41
	v_add_f32_e32 v40, 1.0, v40
	v_add_f32_e32 v41, 1.0, v41
	v_rcp_f32_e32 v40, v40
	v_rcp_f32_e32 v41, v41
	s_nop 0
	v_pk_mul_f32 v[34:35], v[34:35], v[40:41]
	s_nop 0
	v_pk_mul_f32 v[40:41], v[36:37], v[34:35]
	v_cvt_pk_bf16_f32 v36, v38, v39
	v_mad_u64_u32 v[38:39], s[20:21], v46, s89, v[130:131]
	v_cvt_pk_bf16_f32 v37, v40, v41
	v_mov_b32_e32 v40, v39
	v_mad_u64_u32 v[40:41], s[20:21], v47, s89, v[40:41]
	v_cvt_pk_bf16_f32 v34, v42, v43
	v_cvt_pk_bf16_f32 v35, v44, v45
	v_mov_b32_e32 v39, v40
	s_mov_b64 exec, s[98:99]
	global_store_dwordx4 v[38:39], v[34:37], off sc1
	s_mov_b64 exec, s[100:101]
	global_store_dwordx4 v[38:39], v[34:37], off
	s_mov_b64 exec, -1
	s_mov_b64 s[20:21], 0xa0
	s_nop 0
	v_mul_f32_e32 v34, 0xbfb8aa3b, v30
	v_mul_f32_e32 v35, 0xbfb8aa3b, v31
	v_exp_f32_e32 v34, v34
	v_exp_f32_e32 v35, v35
	v_add_f32_e32 v34, 1.0, v34
	v_add_f32_e32 v35, 1.0, v35
	v_rcp_f32_e32 v34, v34
	v_rcp_f32_e32 v35, v35
	s_nop 0
	v_pk_mul_f32 v[30:31], v[30:31], v[34:35]
	s_nop 0
	v_pk_mul_f32 v[26:27], v[26:27], v[30:31]
	v_pk_mul_f32 v[30:31], v[32:33], v[134:135] op_sel_hi:[1,0]
	s_nop 0
	v_mul_f32_e32 v32, 0xbfb8aa3b, v30
	v_mul_f32_e32 v33, 0xbfb8aa3b, v31
	v_exp_f32_e32 v32, v32
	v_exp_f32_e32 v33, v33
	v_add_f32_e32 v32, 1.0, v32
	v_add_f32_e32 v33, 1.0, v33
	v_rcp_f32_e32 v32, v32
	v_rcp_f32_e32 v33, v33
	s_nop 0
	v_pk_mul_f32 v[30:31], v[30:31], v[32:33]
	s_nop 0
	v_pk_mul_f32 v[28:29], v[28:29], v[30:31]
	v_mul_f32_e32 v30, 0xbfb8aa3b, v22
	v_mul_f32_e32 v31, 0xbfb8aa3b, v23
	v_exp_f32_e32 v30, v30
	v_exp_f32_e32 v31, v31
	v_add_f32_e32 v30, 1.0, v30
	v_add_f32_e32 v31, 1.0, v31
	v_rcp_f32_e32 v30, v30
	v_rcp_f32_e32 v31, v31
	s_nop 0
	v_pk_mul_f32 v[22:23], v[22:23], v[30:31]
	s_nop 0
	v_pk_mul_f32 v[22:23], v[18:19], v[22:23]
	v_pk_mul_f32 v[18:19], v[24:25], v[134:135] op_sel_hi:[1,0]
	v_lshl_add_u64 v[30:31], v[170:171], 0, s[20:21]
	v_mul_f32_e32 v24, 0xbfb8aa3b, v18
	v_mul_f32_e32 v25, 0xbfb8aa3b, v19
	v_exp_f32_e32 v24, v24
	v_exp_f32_e32 v25, v25
	v_add_f32_e32 v24, 1.0, v24
	v_add_f32_e32 v25, 1.0, v25
	v_rcp_f32_e32 v24, v24
	v_rcp_f32_e32 v25, v25
	s_nop 0
	v_pk_mul_f32 v[18:19], v[18:19], v[24:25]
	s_nop 0
	v_pk_mul_f32 v[24:25], v[20:21], v[18:19]
	v_cvt_pk_bf16_f32 v20, v22, v23
	v_mad_u64_u32 v[22:23], s[20:21], v30, s89, v[130:131]
	v_cvt_pk_bf16_f32 v21, v24, v25
	v_mov_b32_e32 v24, v23
	v_mad_u64_u32 v[24:25], s[20:21], v31, s89, v[24:25]
	v_cvt_pk_bf16_f32 v18, v26, v27
	v_cvt_pk_bf16_f32 v19, v28, v29
	v_mov_b32_e32 v23, v24
	s_mov_b64 exec, s[98:99]
	global_store_dwordx4 v[22:23], v[18:21], off sc1
	s_mov_b64 exec, s[100:101]
	global_store_dwordx4 v[22:23], v[18:21], off
	s_mov_b64 exec, -1
	s_mov_b64 s[20:21], 0xb0
	s_nop 0
	v_mul_f32_e32 v18, 0xbfb8aa3b, v14
	v_mul_f32_e32 v19, 0xbfb8aa3b, v15
	v_exp_f32_e32 v18, v18
	v_exp_f32_e32 v19, v19
	v_add_f32_e32 v18, 1.0, v18
	v_add_f32_e32 v19, 1.0, v19
	v_rcp_f32_e32 v18, v18
	v_rcp_f32_e32 v19, v19
	s_nop 0
	v_pk_mul_f32 v[14:15], v[14:15], v[18:19]
	s_nop 0
	v_pk_mul_f32 v[10:11], v[10:11], v[14:15]
	v_pk_mul_f32 v[14:15], v[16:17], v[132:133] op_sel_hi:[1,0]
	s_nop 0
	v_mul_f32_e32 v16, 0xbfb8aa3b, v14
	v_mul_f32_e32 v17, 0xbfb8aa3b, v15
	v_exp_f32_e32 v16, v16
	v_exp_f32_e32 v17, v17
	v_add_f32_e32 v16, 1.0, v16
	v_add_f32_e32 v17, 1.0, v17
	v_rcp_f32_e32 v16, v16
	v_rcp_f32_e32 v17, v17
	s_nop 0
	v_pk_mul_f32 v[14:15], v[14:15], v[16:17]
	s_nop 0
	v_pk_mul_f32 v[12:13], v[12:13], v[14:15]
	v_mul_f32_e32 v14, 0xbfb8aa3b, v6
	v_mul_f32_e32 v15, 0xbfb8aa3b, v7
	v_exp_f32_e32 v14, v14
	v_exp_f32_e32 v15, v15
	v_add_f32_e32 v14, 1.0, v14
	v_add_f32_e32 v15, 1.0, v15
	v_rcp_f32_e32 v14, v14
	v_rcp_f32_e32 v15, v15
	s_nop 0
	v_pk_mul_f32 v[6:7], v[6:7], v[14:15]
	s_nop 0
	v_pk_mul_f32 v[6:7], v[2:3], v[6:7]
	v_pk_mul_f32 v[2:3], v[8:9], v[132:133] op_sel_hi:[1,0]
	v_lshl_add_u64 v[14:15], v[170:171], 0, s[20:21]
	v_mul_f32_e32 v8, 0xbfb8aa3b, v2
	v_mul_f32_e32 v9, 0xbfb8aa3b, v3
	v_exp_f32_e32 v8, v8
	v_exp_f32_e32 v9, v9
	v_add_f32_e32 v8, 1.0, v8
	v_add_f32_e32 v9, 1.0, v9
	v_rcp_f32_e32 v8, v8
	v_rcp_f32_e32 v9, v9
	s_nop 0
	v_pk_mul_f32 v[2:3], v[2:3], v[8:9]
	s_nop 0
	v_pk_mul_f32 v[8:9], v[4:5], v[2:3]
	v_cvt_pk_bf16_f32 v4, v6, v7
	v_mad_u64_u32 v[6:7], s[20:21], v14, s89, v[130:131]
	v_cvt_pk_bf16_f32 v5, v8, v9
	v_mov_b32_e32 v8, v7
	v_mad_u64_u32 v[8:9], s[20:21], v15, s89, v[8:9]
	v_cvt_pk_bf16_f32 v2, v10, v11
	v_cvt_pk_bf16_f32 v3, v12, v13
	v_mov_b32_e32 v7, v8
	s_mov_b64 s[20:21], -1
	s_mov_b64 exec, s[98:99]
	global_store_dwordx4 v[6:7], v[2:5], off sc1
	s_mov_b64 exec, s[100:101]
	global_store_dwordx4 v[6:7], v[2:5], off
	s_mov_b64 exec, -1
	s_cbranch_vccnz .LBB0_2071
	s_andn2_b64 vcc, exec, s[4:5]
	s_cbranch_vccnz .LBB0_2070
	s_barrier
	s_branch .LBB0_2070
